# P0 rows loop: RMSNorm gain loads hoisted out of the loop (no in-loop reloads/vmcnt(0) drains)
# baseline (speedup 1.0000x reference)
.LBB0_36:
	s_add_u32 s18, s52, 0x1000000
	s_addc_u32 s19, s53, 0
	s_add_u32 s44, s52, 0x3000000
	s_addc_u32 s45, s53, 0
	s_cmpk_gt_i32 s56, 0x3fff
	s_cbranch_scc1 .LBB0_39
	v_lshlrev_b32_e32 v8, 4, v1
	v_mbcnt_lo_u32_b32 v1, -1, 0
	v_mov_b32_e32 v9, 0
	v_mbcnt_hi_u32_b32 v1, -1, v1
	v_lshl_add_u64 v[2:3], s[12:13], 0, v[8:9]
	v_lshl_add_u64 v[4:5], s[16:17], 0, v[8:9]
	v_lshl_add_u64 v[6:7], s[14:15], 0, v[8:9]
	v_and_b32_e32 v8, 64, v1
	v_add_u32_e32 v8, 64, v8
	v_xor_b32_e32 v10, 1, v1
	v_cmp_lt_i32_e32 vcc, v10, v8
	s_mov_b32 s14, 0x3a800000
	s_mov_b32 s15, 0x800000
	v_cndmask_b32_e32 v10, v1, v10, vcc
	v_lshlrev_b32_e32 v11, 2, v10
	v_xor_b32_e32 v10, 2, v1
	v_cmp_lt_i32_e32 vcc, v10, v8
	s_nop 1
	v_cndmask_b32_e32 v10, v1, v10, vcc
	v_lshlrev_b32_e32 v12, 2, v10
	v_xor_b32_e32 v10, 4, v1
	v_cmp_lt_i32_e32 vcc, v10, v8
	s_nop 1
	v_cndmask_b32_e32 v10, v1, v10, vcc
	v_lshlrev_b32_e32 v13, 2, v10
	v_xor_b32_e32 v10, 8, v1
	v_cmp_lt_i32_e32 vcc, v10, v8
	s_nop 1
	v_cndmask_b32_e32 v10, v1, v10, vcc
	v_lshlrev_b32_e32 v14, 2, v10
	v_xor_b32_e32 v10, 16, v1
	v_cmp_lt_i32_e32 vcc, v10, v8
	s_nop 1
	v_cndmask_b32_e32 v10, v1, v10, vcc
	v_lshlrev_b32_e32 v15, 2, v10
	v_xor_b32_e32 v10, 32, v1
	v_cmp_lt_i32_e32 vcc, v10, v8
	s_nop 1
	v_cndmask_b32_e32 v1, v1, v10, vcc
	v_lshlrev_b32_e32 v16, 2, v1
	v_mov_b32_e32 v1, v9
	v_lshl_add_u64 v[8:9], s[18:19], 0, v[0:1]
	v_lshl_add_u64 v[0:1], s[44:45], 0, v[0:1]
	v_mov_b32_e32 v10, 0x358637bd
	global_load_dwordx4 v[96:99], v[4:5], off
	global_load_dwordx4 v[100:103], v[4:5], off offset:1024
	global_load_dwordx4 v[104:107], v[4:5], off offset:2048
	global_load_dwordx4 v[108:111], v[4:5], off offset:3072
	s_waitcnt vmcnt(0)
.LBB0_38:
	s_add_i32 s28, s56, s58
	s_cmpk_lt_i32 s28, 0x4000
	s_cselect_b32 s16, s28, s56
	s_ashr_i32 s57, s56, 31
	s_lshl_b64 s[46:47], s[56:57], 12
	v_lshl_add_u64 v[34:35], v[2:3], 0, s[46:47]
	s_ashr_i32 s17, s16, 31
	global_load_dwordx4 v[22:25], v[34:35], off
	global_load_dwordx4 v[26:29], v[34:35], off offset:1024
	global_load_dwordx4 v[30:33], v[34:35], off offset:3072
	s_nop 0
	global_load_dwordx4 v[34:37], v[34:35], off offset:2048
	s_lshl_b64 s[0:1], s[56:57], 10
	s_lshl_b64 s[50:51], s[16:17], 12
	s_lshl_b64 s[46:47], s[16:17], 10
	v_lshl_add_u64 v[38:39], v[6:7], 0, s[0:1]
	v_lshl_add_u64 v[64:65], v[2:3], 0, s[50:51]
	global_load_dwordx4 v[38:41], v[38:39], off nt
	v_lshl_add_u64 v[66:67], v[6:7], 0, s[46:47]
	global_load_dwordx4 v[42:45], v[64:65], off
	global_load_dwordx4 v[46:49], v[64:65], off offset:1024
	global_load_dwordx4 v[50:53], v[64:65], off offset:3072
	global_load_dwordx4 v[54:57], v[64:65], off offset:2048
	global_load_dwordx4 v[58:61], v[66:67], off nt
	s_lshl_b64 s[0:1], s[16:17], 11
	v_lshl_add_u64 v[68:69], v[8:9], 0, s[0:1]
	s_lshl_b64 s[48:49], s[56:57], 11
	v_lshl_add_u64 v[62:63], v[8:9], 0, s[48:49]
	s_waitcnt vmcnt(9)
	v_pk_mul_f32 v[64:65], v[24:25], v[24:25]
	v_pk_mul_f32 v[66:67], v[22:23], v[22:23]
	s_waitcnt vmcnt(8)
	v_pk_mul_f32 v[70:71], v[28:29], v[28:29]
	v_pk_mul_f32 v[72:73], v[26:27], v[26:27]
	s_waitcnt vmcnt(6)
	v_mul_f32_e32 v74, v35, v35
	v_mul_f32_e32 v76, v37, v37
	v_pk_mov_b32 v[78:79], v[66:67], v[64:65] op_sel:[1,0]
	v_mov_b32_e32 v67, v65
	s_waitcnt vmcnt(4)
	v_pk_mul_f32 v[64:65], v[44:45], v[44:45]
	v_pk_mul_f32 v[80:81], v[42:43], v[42:43]
	v_pk_mov_b32 v[82:83], v[72:73], v[70:71] op_sel:[1,0]
	v_mov_b32_e32 v73, v71
	s_waitcnt vmcnt(3)
	v_pk_mul_f32 v[70:71], v[48:49], v[48:49]
	v_pk_mul_f32 v[84:85], v[46:47], v[46:47]
	v_mul_f32_e32 v89, v32, v32
	v_mul_f32_e32 v90, v33, v33
	v_pk_fma_f32 v[74:75], v[34:35], v[34:35], v[74:75] op_sel_hi:[1,1,0]
	v_pk_fma_f32 v[76:77], v[36:37], v[36:37], v[76:77] op_sel_hi:[1,1,0]
	v_pk_add_f32 v[66:67], v[78:79], v[66:67]
	v_pk_mov_b32 v[78:79], v[80:81], v[64:65] op_sel:[1,0]
	v_mov_b32_e32 v81, v65
	v_pk_add_f32 v[64:65], v[82:83], v[72:73]
	v_pk_mov_b32 v[72:73], v[84:85], v[70:71] op_sel:[1,0]
	v_mov_b32_e32 v85, v71
	v_mul_f32_e32 v87, v31, v31
	s_waitcnt vmcnt(0)
	v_mul_f32_e32 v86, v55, v55
	v_mul_f32_e32 v88, v57, v57
	v_mov_b32_e32 v75, v89
	v_mov_b32_e32 v77, v90
	v_pk_add_f32 v[78:79], v[78:79], v[80:81]
	v_pk_add_f32 v[72:73], v[72:73], v[84:85]
	v_mul_f32_e32 v17, v30, v30
	v_mul_f32_e32 v91, v50, v50
	v_mul_f32_e32 v92, v51, v51
	v_mul_f32_e32 v93, v52, v52
	v_mul_f32_e32 v94, v53, v53
	v_pk_fma_f32 v[70:71], v[54:55], v[54:55], v[86:87] op_sel_hi:[1,1,0]
	v_pk_fma_f32 v[82:83], v[56:57], v[56:57], v[88:89] op_sel_hi:[1,1,0]
	v_pk_add_f32 v[66:67], v[66:67], v[66:67] op_sel:[0,1] op_sel_hi:[1,0]
	v_pk_add_f32 v[64:65], v[64:65], v[64:65] op_sel:[0,1] op_sel_hi:[1,0]
	v_pk_add_f32 v[74:75], v[74:75], v[76:77]
	v_pk_add_f32 v[76:77], v[78:79], v[78:79] op_sel:[0,1] op_sel_hi:[1,0]
	v_pk_add_f32 v[72:73], v[72:73], v[72:73] op_sel:[0,1] op_sel_hi:[1,0]
	v_mov_b32_e32 v71, v93
	v_mov_b32_e32 v83, v94
	v_mov_b32_e32 v67, v17
	v_mov_b32_e32 v65, v87
	v_mov_b32_e32 v77, v91
	v_mov_b32_e32 v73, v92
	v_pk_add_f32 v[70:71], v[70:71], v[82:83]
	v_pk_add_f32 v[64:65], v[66:67], v[64:65]
	v_pk_add_f32 v[66:67], v[76:77], v[72:73]
	v_pk_add_f32 v[64:65], v[64:65], v[74:75]
	v_pk_add_f32 v[66:67], v[66:67], v[70:71]
	v_mov_b32_e32 v71, v64
	v_mov_b32_e32 v70, v66
	v_mov_b32_e32 v64, v67
	v_pk_add_f32 v[64:65], v[70:71], v[64:65]
	ds_bpermute_b32 v67, v11, v65
	ds_bpermute_b32 v66, v11, v64
	s_waitcnt lgkmcnt(0)
	v_pk_add_f32 v[64:65], v[64:65], v[66:67]
	ds_bpermute_b32 v67, v12, v65
	ds_bpermute_b32 v66, v12, v64
	s_waitcnt lgkmcnt(0)
	v_pk_add_f32 v[64:65], v[64:65], v[66:67]
	ds_bpermute_b32 v67, v13, v65
	ds_bpermute_b32 v66, v13, v64
	s_waitcnt lgkmcnt(0)
	v_pk_add_f32 v[64:65], v[64:65], v[66:67]
	ds_bpermute_b32 v67, v14, v65
	ds_bpermute_b32 v66, v14, v64
	s_waitcnt lgkmcnt(0)
	v_pk_add_f32 v[64:65], v[64:65], v[66:67]
	ds_bpermute_b32 v67, v15, v65
	ds_bpermute_b32 v66, v15, v64
	s_waitcnt lgkmcnt(0)
	v_pk_add_f32 v[64:65], v[64:65], v[66:67]
	ds_bpermute_b32 v67, v16, v65
	ds_bpermute_b32 v66, v16, v64
	s_waitcnt lgkmcnt(0)
	v_pk_add_f32 v[64:65], v[64:65], v[66:67]
	s_nop 0
	v_pk_fma_f32 v[64:65], v[64:65], s[14:15], v[10:11] op_sel_hi:[1,0,0]
	s_nop 0
	v_mul_f32_e32 v17, 0x4b800000, v65
	v_cmp_gt_f32_e64 s[0:1], s15, v65
	v_mul_f32_e32 v66, 0x4b800000, v64
	v_cmp_gt_f32_e32 vcc, s15, v64
	v_cndmask_b32_e64 v17, v65, v17, s[0:1]
	v_rsq_f32_e32 v17, v17
	v_cndmask_b32_e32 v64, v64, v66, vcc
	v_rsq_f32_e32 v65, v64
	v_mul_f32_e32 v64, 0x45800000, v17
	v_cndmask_b32_e64 v64, v17, v64, s[0:1]
	v_mul_f32_e32 v66, 0x45800000, v65
	v_cndmask_b32_e32 v66, v65, v66, vcc
	v_pk_mul_f32 v[22:23], v[64:65], v[22:23] op_sel_hi:[0,1]
	v_pk_mul_f32 v[24:25], v[64:65], v[24:25] op_sel_hi:[0,1]
	v_pk_mul_f32 v[42:43], v[66:67], v[42:43] op_sel_hi:[0,1]
	v_pk_mul_f32 v[44:45], v[66:67], v[44:45] op_sel_hi:[0,1]
	v_pk_mul_f32 v[24:25], v[24:25], v[98:99]
	v_pk_mul_f32 v[22:23], v[22:23], v[96:97]
	v_pk_mul_f32 v[20:21], v[44:45], v[98:99]
	v_pk_mul_f32 v[18:19], v[42:43], v[96:97]
	v_cvt_pk_bf16_f32 v22, v22, v23
	v_cvt_pk_bf16_f32 v23, v24, v25
	v_cvt_pk_bf16_f32 v18, v18, v19
	v_cvt_pk_bf16_f32 v19, v20, v21
	global_store_dwordx2 v[62:63], v[22:23], off
	global_store_dwordx2 v[68:69], v[18:19], off
	v_pk_mul_f32 v[22:23], v[64:65], v[26:27] op_sel_hi:[0,1]
	v_pk_mul_f32 v[24:25], v[64:65], v[28:29] op_sel_hi:[0,1]
	v_pk_mul_f32 v[26:27], v[66:67], v[46:47] op_sel_hi:[0,1]
	v_pk_mul_f32 v[28:29], v[66:67], v[48:49] op_sel_hi:[0,1]
	s_lshl_b64 s[0:1], s[56:57], 9
	v_pk_mul_f32 v[30:31], v[64:65], v[30:31] op_sel_hi:[0,1]
	v_pk_mul_f32 v[32:33], v[64:65], v[32:33] op_sel_hi:[0,1]
	s_add_i32 s56, s28, s58
	v_pk_mul_f32 v[24:25], v[24:25], v[102:103]
	v_pk_mul_f32 v[22:23], v[22:23], v[100:101]
	v_pk_mul_f32 v[20:21], v[28:29], v[102:103]
	v_pk_mul_f32 v[18:19], v[26:27], v[100:101]
	v_cvt_pk_bf16_f32 v22, v22, v23
	v_cvt_pk_bf16_f32 v23, v24, v25
	v_cvt_pk_bf16_f32 v18, v18, v19
	v_cvt_pk_bf16_f32 v19, v20, v21
	global_store_dwordx2 v[62:63], v[22:23], off offset:512
	global_store_dwordx2 v[68:69], v[18:19], off offset:512
	v_pk_mul_f32 v[22:23], v[64:65], v[34:35] op_sel_hi:[0,1]
	v_pk_mul_f32 v[24:25], v[64:65], v[36:37] op_sel_hi:[0,1]
	v_pk_mul_f32 v[26:27], v[66:67], v[54:55] op_sel_hi:[0,1]
	v_pk_mul_f32 v[28:29], v[66:67], v[56:57] op_sel_hi:[0,1]
	v_pk_mul_f32 v[34:35], v[66:67], v[50:51] op_sel_hi:[0,1]
	v_pk_mul_f32 v[36:37], v[66:67], v[52:53] op_sel_hi:[0,1]
	v_pk_mul_f32 v[24:25], v[24:25], v[106:107]
	v_pk_mul_f32 v[22:23], v[22:23], v[104:105]
	v_pk_mul_f32 v[20:21], v[28:29], v[106:107]
	v_pk_mul_f32 v[18:19], v[26:27], v[104:105]
	v_cvt_pk_bf16_f32 v22, v22, v23
	v_cvt_pk_bf16_f32 v23, v24, v25
	v_cvt_pk_bf16_f32 v18, v18, v19
	v_cvt_pk_bf16_f32 v19, v20, v21
	global_store_dwordx2 v[62:63], v[22:23], off offset:1024
	global_store_dwordx2 v[68:69], v[18:19], off offset:1024
	v_lshl_add_u64 v[22:23], v[0:1], 0, s[0:1]
	s_lshl_b64 s[0:1], s[16:17], 9
	s_cmpk_gt_i32 s56, 0x3fff
	v_lshl_add_u64 v[24:25], v[0:1], 0, s[0:1]
	v_cvt_pk_bf16_f32 v26, v38, v39
	v_cvt_pk_bf16_f32 v27, v40, v41
	v_cvt_pk_bf16_f32 v28, v58, v59
	v_cvt_pk_bf16_f32 v29, v60, v61
	v_pk_mul_f32 v[32:33], v[32:33], v[110:111]
	v_pk_mul_f32 v[30:31], v[30:31], v[108:109]
	v_pk_mul_f32 v[20:21], v[36:37], v[110:111]
	v_pk_mul_f32 v[18:19], v[34:35], v[108:109]
	v_cvt_pk_bf16_f32 v30, v30, v31
	v_cvt_pk_bf16_f32 v31, v32, v33
	v_cvt_pk_bf16_f32 v18, v18, v19
	v_cvt_pk_bf16_f32 v19, v20, v21
	global_store_dwordx2 v[62:63], v[30:31], off offset:1536
	global_store_dwordx2 v[68:69], v[18:19], off offset:1536
	global_store_dwordx2 v[22:23], v[26:27], off
	global_store_dwordx2 v[24:25], v[28:29], off
	s_cbranch_scc0 .LBB0_38
